# v22: v17 + big-GEMM unit prologue: K-tile 1 stage loads issued together with K-tile 0 (4 of 10 instances: up l0, up l1, in-proj l1, merged down)
# baseline (speedup 1.0000x reference)
.LBB0_1424:
	s_cmp_lt_i32 s80, 0
	s_cselect_b64 s[2:3], -1, 0
	s_lshl_b32 s4, s80, 6
	v_or_b32_e32 v3, s4, v228
	v_cndmask_b32_e64 v3, v3, v228, s[2:3]
	s_ashr_i32 s39, s38, 31
	s_ashr_i32 s35, s34, 31
	v_lshl_or_b32 v212, v3, 11, v229
	v_add_u32_e32 v3, s4, v232
	s_lshl_b64 s[4:5], s[38:39], 11
	s_lshl_b64 s[46:47], s[34:35], 19
	s_add_u32 s42, s53, s46
	s_addc_u32 s43, s54, s47
	s_add_i32 s35, s78, 0x10400
	s_add_i32 s39, s78, 0x12400
	v_cndmask_b32_e64 v3, v3, v230, s[2:3]
	s_mov_b32 m0, s35
	s_add_u32 s44, s42, 0x40000
	v_lshl_or_b32 v214, v3, 11, v229
	global_load_lds_dwordx4 v212, s[42:43]
	s_mov_b32 m0, s39
	s_addc_u32 s45, s43, 0
	s_add_i32 s81, s78, 0x14400
	global_load_lds_dwordx4 v214, s[42:43]
	v_lshl_add_u64 v[4:5], s[44:45], 0, v[200:201]
	s_mov_b32 m0, s81
	s_add_i32 s82, s78, 0x16400
	global_load_lds_dwordx4 v[4:5], off
	v_lshl_add_u64 v[4:5], s[44:45], 0, v[202:203]
	s_add_u32 s44, s55, s4
	s_mov_b32 m0, s82
	s_addc_u32 s45, s57, s5
	s_add_i32 s83, s78, 0x400
	s_add_i32 s84, s78, 0x2400
	global_load_lds_dwordx4 v[4:5], off
	v_lshl_add_u64 v[4:5], s[44:45], 0, v[200:201]
	s_mov_b32 m0, s83
	s_add_u32 s48, s44, 0x40000
	global_load_lds_dwordx4 v[4:5], off
	v_lshl_add_u64 v[22:23], s[44:45], 0, v[202:203]
	s_mov_b32 m0, s84
	s_addc_u32 s49, s45, 0
	s_add_i32 s85, s78, 0x4400
	global_load_lds_dwordx4 v[22:23], off
	v_lshl_add_u64 v[24:25], s[48:49], 0, v[200:201]
	s_mov_b32 m0, s85
	s_add_i32 s86, s78, 0x6400
	global_load_lds_dwordx4 v[24:25], off
	v_lshl_add_u64 v[24:25], s[48:49], 0, v[202:203]
	s_mov_b32 m0, s86
	s_andn2_b64 vcc, exec, s[14:15]
	global_load_lds_dwordx4 v[24:25], off
	v_mov_b32_e32 v213, v2
	v_lshl_add_u64 v[24:25], s[42:43], 0, v[212:213]
	v_mov_b32_e32 v215, v2
	s_add_i32 s87, s78, 0x18400
	v_lshl_add_u64 v[26:27], s[42:43], 0, v[214:215]
	v_lshl_add_u64 v[24:25], v[24:25], 0, s[26:27]
	s_mov_b32 m0, s87
	s_add_i32 s88, s78, 0x1a400
	global_load_lds_dwordx4 v[24:25], off
	v_lshl_add_u64 v[24:25], v[26:27], 0, s[26:27]
	s_mov_b32 m0, s88
	s_add_i32 s89, s78, 0x8400
	s_add_i32 s90, s78, 0xa400
	global_load_lds_dwordx4 v[24:25], off
	v_lshl_add_u64 v[4:5], v[4:5], 0, s[26:27]
	s_mov_b32 m0, s89
	s_add_u32 s48, s42, 0x40080
	global_load_lds_dwordx4 v[4:5], off
	v_lshl_add_u64 v[4:5], v[22:23], 0, s[26:27]
	s_mov_b32 m0, s90
	s_addc_u32 s49, s43, 0
	s_add_i32 s91, s78, 0x1c400
	global_load_lds_dwordx4 v[4:5], off
	v_lshl_add_u64 v[4:5], s[48:49], 0, v[200:201]
	s_mov_b32 m0, s91
	s_add_i32 s92, s78, 0x1e400
	global_load_lds_dwordx4 v[4:5], off
	v_lshl_add_u64 v[4:5], s[48:49], 0, v[202:203]
	s_mov_b32 m0, s92
	s_nop 0
	global_load_lds_dwordx4 v[4:5], off
	s_cbranch_vccnz .LBB0_1426
	s_barrier
.LBB0_1426:
	s_waitcnt vmcnt(8)
	s_barrier
	s_add_u32 s93, s71, s46
	s_waitcnt vmcnt(6)
	s_addc_u32 s94, s72, s47
	v_mov_b32_e32 v4, v2
	v_mov_b32_e32 v5, v2
	s_add_u32 s95, s6, s4
	v_mov_b32_e32 v3, v2
	v_mov_b32_e32 v70, 0
	v_mov_b64_e32 v[52:53], v[4:5]
	v_mov_b64_e32 v[48:49], v[4:5]
	v_mov_b64_e32 v[44:45], v[4:5]
	v_mov_b64_e32 v[40:41], v[4:5]
	v_mov_b64_e32 v[36:37], v[4:5]
	v_mov_b64_e32 v[32:33], v[4:5]
	v_mov_b64_e32 v[28:29], v[4:5]
	v_mov_b64_e32 v[24:25], v[4:5]
	v_mov_b64_e32 v[116:117], v[4:5]
	v_mov_b64_e32 v[112:113], v[4:5]
	v_mov_b64_e32 v[108:109], v[4:5]
	v_mov_b64_e32 v[104:105], v[4:5]
	s_waitcnt lgkmcnt(0)
	v_mov_b64_e32 v[100:101], v[4:5]
	v_mov_b64_e32 v[96:97], v[4:5]
	v_mov_b64_e32 v[92:93], v[4:5]
	v_mov_b64_e32 v[88:89], v[4:5]
	v_lshl_add_u64 v[216:217], v[204:205], 0, s[4:5]
	v_lshl_add_u64 v[218:219], v[206:207], 0, s[4:5]
	s_addc_u32 s96, s7, s5
	s_mov_b32 s97, -2
	s_mov_b64 s[46:47], 0
	v_mov_b64_e32 v[50:51], v[2:3]
	v_mov_b64_e32 v[46:47], v[2:3]
	v_mov_b64_e32 v[42:43], v[2:3]
	v_mov_b64_e32 v[38:39], v[2:3]
	v_mov_b64_e32 v[34:35], v[2:3]
	v_mov_b64_e32 v[30:31], v[2:3]
	v_mov_b64_e32 v[26:27], v[2:3]
	v_mov_b64_e32 v[22:23], v[2:3]
	v_mov_b64_e32 v[114:115], v[2:3]
	v_mov_b64_e32 v[110:111], v[2:3]
	v_mov_b64_e32 v[106:107], v[2:3]
	v_mov_b64_e32 v[102:103], v[2:3]
	v_mov_b64_e32 v[98:99], v[2:3]
	v_mov_b64_e32 v[94:95], v[2:3]
	v_mov_b64_e32 v[90:91], v[2:3]
	v_mov_b64_e32 v[86:87], v[2:3]
	v_mov_b32_e32 v71, v70
	v_mov_b32_e32 v72, v70
	v_mov_b32_e32 v73, v70
	v_mov_b32_e32 v82, v70
	v_mov_b32_e32 v83, v70
	v_mov_b32_e32 v84, v70
	v_mov_b32_e32 v85, v70
	v_mov_b32_e32 v74, v70
	v_mov_b32_e32 v75, v70
	v_mov_b32_e32 v76, v70
	v_mov_b32_e32 v77, v70
	v_mov_b32_e32 v78, v70
	v_mov_b32_e32 v79, v70
	v_mov_b32_e32 v80, v70
	v_mov_b32_e32 v81, v70
	v_mov_b32_e32 v62, v70
	v_mov_b32_e32 v63, v70
	v_mov_b32_e32 v64, v70
	v_mov_b32_e32 v65, v70
	v_mov_b32_e32 v66, v70
	v_mov_b32_e32 v67, v70
	v_mov_b32_e32 v68, v70
	v_mov_b32_e32 v69, v70
	v_mov_b32_e32 v54, v70
	v_mov_b32_e32 v55, v70
	v_mov_b32_e32 v56, v70
	v_mov_b32_e32 v57, v70
	v_mov_b32_e32 v58, v70
	v_mov_b32_e32 v59, v70
	v_mov_b32_e32 v60, v70
	v_mov_b32_e32 v61, v70
	v_mov_b32_e32 v142, v70
	v_mov_b32_e32 v143, v70
	v_mov_b32_e32 v144, v70
	v_mov_b32_e32 v145, v70
	v_mov_b32_e32 v146, v70
	v_mov_b32_e32 v147, v70
	v_mov_b32_e32 v148, v70
	v_mov_b32_e32 v149, v70
	v_mov_b32_e32 v134, v70
	v_mov_b32_e32 v135, v70
	v_mov_b32_e32 v136, v70
	v_mov_b32_e32 v137, v70
	v_mov_b32_e32 v138, v70
	v_mov_b32_e32 v139, v70
	v_mov_b32_e32 v140, v70
	v_mov_b32_e32 v141, v70
	v_mov_b32_e32 v126, v70
	v_mov_b32_e32 v127, v70
	v_mov_b32_e32 v128, v70
	v_mov_b32_e32 v129, v70
	v_mov_b32_e32 v130, v70
	v_mov_b32_e32 v131, v70
	v_mov_b32_e32 v132, v70
	v_mov_b32_e32 v133, v70
	v_mov_b32_e32 v118, v70
	v_mov_b32_e32 v119, v70
	v_mov_b32_e32 v120, v70
	v_mov_b32_e32 v121, v70
	v_mov_b32_e32 v122, v70
	v_mov_b32_e32 v123, v70
	v_mov_b32_e32 v124, v70
	v_mov_b32_e32 v125, v70
	s_barrier
	s_branch .LBB0_1428

.LBB0_2529:
	s_add_u32 s48, s8, 0x3128000
	s_addc_u32 s49, s9, 0
	v_lshlrev_b32_e32 v1, 4, v0
	s_add_u32 s50, s8, 0x29c8000
	v_and_b32_e32 v2, 32, v0
	v_or_b32_e32 v18, 0x2000, v1
	s_addc_u32 s51, s9, 0
	v_bfe_u32 v17, v0, 2, 4
	v_bitop3_b32 v16, v1, v2, 48 bitop3:0x6c
	v_lshrrev_b32_e32 v1, 7, v18
	s_movk_i32 s3, 0x70
	s_ashr_i32 s13, s12, 31
	s_lshr_b32 s2, s33, 8
	v_and_or_b32 v1, v1, s3, v17
	s_lshl_b32 s3, s68, 10
	s_lshl_b64 s[10:11], s[12:13], 19
	s_lshl_b32 s6, s67, 1
	v_lshrrev_b32_e32 v3, 3, v0
	s_cmp_gt_i32 s69, 0
	v_and_or_b32 v4, v3, 48, v17
	v_and_b32_e32 v3, 64, v0
	v_lshlrev_b32_e32 v1, 11, v1
	s_cselect_b64 s[4:5], -1, 0
	v_or3_b32 v202, v3, v1, v16
	v_cndmask_b32_e64 v1, 0, 1, s[4:5]
	v_lshlrev_b32_e32 v2, 11, v4
	v_readfirstlane_b32 s4, v1
	s_or_b32 s4, s6, s4
	s_ashr_i32 s5, s4, 31
	s_lshl_b64 s[4:5], s[4:5], 18
	s_add_u32 s4, s50, s4
	s_addc_u32 s5, s51, s5
	s_add_i32 s13, s3, 0
	s_add_i32 s52, s13, 0x10400
	s_add_i32 s53, s13, 0x12400
	s_cmp_gt_i32 s69, -1
	s_cselect_b32 s6, 0, 0x40000
	v_or3_b32 v200, v3, v2, v16
	s_mov_b32 m0, s52
	s_add_u32 s14, s4, s6
	global_load_lds_dwordx4 v200, s[4:5]
	s_mov_b32 m0, s53
	s_addc_u32 s15, s5, 0
	s_add_i32 s54, s13, 0x14400
	s_add_i32 s55, s13, 0x16400
	global_load_lds_dwordx4 v202, s[4:5]
	s_mov_b32 m0, s54
	s_add_u32 s24, s48, s10
	global_load_lds_dwordx4 v200, s[14:15]
	s_mov_b32 m0, s55
	s_addc_u32 s25, s49, s11
	s_add_i32 s57, s13, 0x400
	s_add_i32 s64, s13, 0x2400
	global_load_lds_dwordx4 v202, s[14:15]
	s_mov_b32 m0, s57
	s_add_u32 s10, s24, 0x40000
	global_load_lds_dwordx4 v200, s[24:25]
	s_mov_b32 m0, s64
	s_addc_u32 s11, s25, 0
	s_add_i32 s65, s13, 0x4400
	global_load_lds_dwordx4 v202, s[24:25]
	s_mov_b32 m0, s65
	s_add_i32 s66, s13, 0x6400
	global_load_lds_dwordx4 v200, s[10:11]
	s_mov_b32 m0, s66
	v_mov_b32_e32 v2, 0
	global_load_lds_dwordx4 v202, s[10:11]
	v_mov_b32_e32 v201, v2
	v_mov_b32_e32 v203, v2
	s_cmp_eq_u32 s2, 1
	v_lshrrev_b32_e32 v19, 2, v0
	s_mov_b32 s7, 0
	v_lshl_add_u64 v[14:15], s[4:5], 0, v[200:201]
	v_lshl_add_u64 v[12:13], s[4:5], 0, v[202:203]
	v_lshl_add_u64 v[6:7], s[14:15], 0, v[200:201]
	v_lshl_add_u64 v[4:5], s[14:15], 0, v[202:203]
	v_lshl_add_u64 v[8:9], s[24:25], 0, v[200:201]
	s_cselect_b64 s[14:15], -1, 0
	v_lshl_add_u64 v[10:11], s[24:25], 0, v[202:203]
	s_add_i32 s71, s13, 0x18400
	s_mov_b64 s[16:17], 0x80
	v_lshl_add_u64 v[14:15], v[14:15], 0, s[16:17]
	s_mov_b32 m0, s71
	s_add_i32 s72, s13, 0x1a400
	global_load_lds_dwordx4 v[14:15], off
	v_lshl_add_u64 v[12:13], v[12:13], 0, s[16:17]
	s_mov_b32 m0, s72
	s_add_i32 s73, s13, 0x8400
	global_load_lds_dwordx4 v[12:13], off
	v_lshl_add_u64 v[8:9], v[8:9], 0, s[16:17]
	s_mov_b32 m0, s73
	s_add_i32 s74, s13, 0xa400
	global_load_lds_dwordx4 v[8:9], off
	v_lshl_add_u64 v[8:9], v[10:11], 0, s[16:17]
	s_mov_b32 m0, s74
	s_add_i32 s75, s13, 0x1c400
	global_load_lds_dwordx4 v[8:9], off
	v_lshl_add_u64 v[6:7], v[6:7], 0, s[16:17]
	s_mov_b32 m0, s75
	s_add_i32 s76, s13, 0x1e400
	global_load_lds_dwordx4 v[6:7], off
	v_lshl_add_u64 v[4:5], v[4:5], 0, s[16:17]
	s_mov_b32 m0, s76
	s_nop 0
	global_load_lds_dwordx4 v[4:5], off
	s_cmp_lg_u32 s2, 1
	s_cbranch_scc1 .LBB0_2531
	s_barrier
.LBB0_2531:
	s_add_u32 s8, s8, 0x4928000
	s_addc_u32 s3, s9, 0
	s_waitcnt vmcnt(8)
	s_barrier
	v_and_b32_e32 v20, 15, v0
	v_and_b32_e32 v21, 48, v0
	v_lshl_or_b32 v1, s2, 6, v20
	v_lshl_or_b32 v20, v20, 6, v21
	v_lshlrev_b32_e32 v21, 2, v0
	s_lshl_b32 s2, s2, 13
	v_and_b32_e32 v21, 32, v21
	v_bitop3_b32 v22, v20, s2, v21 bitop3:0xde
	s_lshl_b32 s2, s68, 5
	s_and_b32 s70, s2, 0x60
	s_and_b32 s9, s3, 0xffff
	s_lshl_b32 s2, s70, 7
	s_cmpk_lt_u32 s33, 0x100
	v_bitop3_b32 v20, s2, v20, v21 bitop3:0xf6
	s_cselect_b64 s[18:19], -1, 0
	s_lshl_b32 s2, s22, 1
	s_sub_i32 s2, 0x2a0, s2
	s_cmp_gt_i32 s2, s56
	s_cselect_b64 s[20:21], -1, 0
	s_cmp_lt_i32 s30, s2
	s_cselect_b64 s[2:3], -1, 0
	s_ashr_i32 s23, s30, 1
	s_ashr_i32 s28, s23, 31
	s_mul_hi_i32 s27, s47, s56
	s_add_u32 s26, s22, s23
	s_addc_u32 s27, s27, s28
	s_ashr_i32 s22, s26, 31
	s_lshr_b32 s22, s22, 29
	s_add_i32 s22, s26, s22
	s_ashr_i32 s23, s22, 3
	s_and_b32 s22, s22, -8
	s_sub_i32 s22, s26, s22
	s_cmp_lt_i32 s22, 0
	s_cselect_b32 s28, 43, 42
	s_mul_i32 s22, s28, s22
	s_add_i32 s22, s22, s23
	s_mul_hi_i32 s23, s22, 0x92492493
	s_add_i32 s23, s23, s22
	s_lshr_b32 s28, s23, 31
	s_ashr_i32 s23, s23, 6
	s_add_i32 s23, s23, s28
	s_lshl_b32 s28, s23, 3
	s_sub_i32 s29, 24, s28
	s_min_i32 s29, s29, 8
	s_abs_i32 s34, s29
	v_cvt_f32_u32_e32 v6, s34
	s_sub_i32 s36, 0, s34
	s_mulk_i32 s23, 0x70
	s_sub_i32 s22, s22, s23
	v_rcp_iflag_f32_e32 v6, v6
	s_abs_i32 s35, s22
	s_xor_b32 s23, s22, s29
	s_and_b32 s77, s30, 1
	v_mul_f32_e32 v6, 0x4f7ffffe, v6
	v_cvt_u32_f32_e32 v6, v6
	s_ashr_i32 s78, s30, 31
	s_ashr_i32 s23, s23, 31
	v_lshlrev_b32_e32 v8, 11, v17
	v_readfirstlane_b32 s37, v6
	s_mul_i32 s36, s36, s37
	s_mul_hi_u32 s36, s37, s36
	s_add_i32 s37, s37, s36
	s_mul_hi_u32 s36, s35, s37
	s_mul_i32 s37, s36, s34
	s_sub_i32 s35, s35, s37
	s_add_i32 s37, s36, 1
	s_sub_i32 s38, s35, s34
	s_cmp_ge_u32 s35, s34
	s_cselect_b32 s36, s37, s36
	s_cselect_b32 s35, s38, s35
	s_add_i32 s37, s36, 1
	s_cmp_ge_u32 s35, s34
	s_cselect_b32 s34, s37, s36
	s_xor_b32 s34, s34, s23
	v_lshlrev_b32_e32 v6, 4, v18
	s_sub_i32 s79, s34, s23
	v_and_b32_e32 v6, 0x38000, v6
	s_mul_i32 s23, s79, s29
	v_or3_b32 v6, v16, v6, v8
	s_sub_i32 s80, s22, s23
	v_add_u32_e32 v6, v6, v3
	v_mov_b32_e32 v7, v2
	s_mov_b64 s[22:23], 0x40080
	v_lshl_add_u64 v[204:205], v[6:7], 0, s[22:23]
	v_lshlrev_b32_e32 v6, 8, v0
	v_and_b32_e32 v6, 0x18000, v6
	s_waitcnt vmcnt(6)
	v_or3_b32 v6, v16, v6, v8
	v_mov_b64_e32 v[4:5], 0x150
	v_add_u32_e32 v6, v6, v3
	v_add_u32_e32 v221, 0, v20
	s_mov_b32 s11, 0x20000
	s_mov_b32 s10, 0x5400000
	v_and_b32_e32 v220, 12, v19
	s_add_i32 s80, s80, s28
	v_lshl_add_u64 v[206:207], v[6:7], 0, s[22:23]
	s_xor_b64 s[22:23], s[2:3], -1
	v_cmp_lt_i64_e64 s[2:3], s[26:27], v[4:5]
	v_add_u32_e32 v222, 0x10400, v221
	s_movk_i32 s81, 0xe00
	v_mov_b64_e32 v[208:209], 0x14f
	v_add_u32_e32 v223, 0, v22
	v_mov_b32_e32 v224, 0x38000
	v_mov_b32_e32 v225, 0x70000
	v_mov_b32_e32 v226, 0xa8000
	v_mov_b32_e32 v227, 0x1c0000
	v_mov_b32_e32 v228, 0x1f8000
	v_mov_b32_e32 v229, 0x230000
	v_mov_b32_e32 v230, 0x268000
	s_mov_b64 s[36:37], s[6:7]
	s_mov_b32 s39, s7
	s_barrier
	s_branch .LBB0_2534

.LBB0_3302:
	s_ashr_i32 s7, s6, 31
	s_ashr_i32 s29, s28, 31
	s_lshl_b64 s[40:41], s[6:7], 11
	s_lshl_b64 s[42:43], s[28:29], 19
	s_add_u32 s36, s47, s42
	s_addc_u32 s37, s48, s43
	s_add_i32 s7, s52, 0
	v_lshl_add_u64 v[4:5], s[36:37], 0, v[134:135]
	s_add_i32 m0, s7, 0x10400
	v_lshl_add_u64 v[6:7], s[36:37], 0, v[136:137]
	global_load_lds_dwordx4 v[4:5], off
	s_add_i32 m0, s7, 0x12400
	s_add_u32 s38, s36, 0x40000
	s_addc_u32 s39, s37, 0
	global_load_lds_dwordx4 v[6:7], off
	v_lshl_add_u64 v[8:9], s[38:39], 0, v[134:135]
	s_add_i32 m0, s7, 0x14400
	s_nop 0
	global_load_lds_dwordx4 v[8:9], off
	s_add_i32 m0, s7, 0x16400
	v_lshl_add_u64 v[8:9], s[38:39], 0, v[136:137]
	s_add_u32 s38, s49, s40
	s_addc_u32 s39, s50, s41
	s_add_i32 s29, s7, 0x400
	s_add_i32 s70, s7, 0x2400
	global_load_lds_dwordx4 v[8:9], off
	v_lshl_add_u64 v[8:9], s[38:39], 0, v[134:135]
	s_mov_b32 m0, s29
	s_add_u32 s44, s38, 0x40000
	global_load_lds_dwordx4 v[8:9], off
	v_lshl_add_u64 v[10:11], s[38:39], 0, v[136:137]
	s_mov_b32 m0, s70
	s_addc_u32 s45, s39, 0
	s_add_i32 s71, s7, 0x4400
	global_load_lds_dwordx4 v[10:11], off
	v_lshl_add_u64 v[12:13], s[44:45], 0, v[134:135]
	s_mov_b32 m0, s71
	s_add_i32 s72, s7, 0x6400
	global_load_lds_dwordx4 v[12:13], off
	v_lshl_add_u64 v[12:13], s[44:45], 0, v[136:137]
	s_mov_b32 m0, s72
	s_andn2_b64 vcc, exec, s[16:17]
	global_load_lds_dwordx4 v[12:13], off
	v_lshl_add_u64 v[4:5], v[4:5], 0, s[24:25]
	s_add_i32 m0, s7, 0x18400
	s_nop 0
	global_load_lds_dwordx4 v[4:5], off
	v_lshl_add_u64 v[4:5], v[6:7], 0, s[24:25]
	s_add_i32 m0, s7, 0x1a400
	s_add_i32 s73, s7, 0x8400
	s_add_i32 s74, s7, 0xa400
	global_load_lds_dwordx4 v[4:5], off
	v_lshl_add_u64 v[4:5], v[8:9], 0, s[24:25]
	s_mov_b32 m0, s73
	s_add_u32 s44, s36, 0x40080
	global_load_lds_dwordx4 v[4:5], off
	v_lshl_add_u64 v[4:5], v[10:11], 0, s[24:25]
	s_mov_b32 m0, s74
	s_addc_u32 s45, s37, 0
	global_load_lds_dwordx4 v[4:5], off
	v_lshl_add_u64 v[4:5], s[44:45], 0, v[134:135]
	s_add_i32 m0, s7, 0x1c400
	s_nop 0
	global_load_lds_dwordx4 v[4:5], off
	v_lshl_add_u64 v[4:5], s[44:45], 0, v[136:137]
	s_add_i32 m0, s7, 0x1e400
	s_nop 0
	global_load_lds_dwordx4 v[4:5], off
	s_cbranch_vccnz .LBB0_3304
	s_barrier
.LBB0_3304:
	s_waitcnt vmcnt(8)
	s_barrier
	v_mov_b32_e32 v36, 0
	s_add_u32 s75, s57, s42
	s_waitcnt vmcnt(6)
	s_addc_u32 s76, s64, s43
	s_add_u32 s77, s8, s40
	v_lshl_add_u64 v[68:69], v[138:139], 0, s[40:41]
	v_lshl_add_u64 v[150:151], v[140:141], 0, s[40:41]
	s_addc_u32 s78, s9, s41
	s_mov_b32 s79, -2
	s_mov_b64 s[40:41], 0
	v_mov_b32_e32 v37, v36
	v_mov_b32_e32 v38, v36
	v_mov_b32_e32 v39, v36
	v_mov_b32_e32 v40, v36
	v_mov_b32_e32 v41, v36
	v_mov_b32_e32 v42, v36
	v_mov_b32_e32 v43, v36
	v_mov_b32_e32 v20, v36
	v_mov_b32_e32 v21, v36
	v_mov_b32_e32 v22, v36
	v_mov_b32_e32 v23, v36
	v_mov_b32_e32 v24, v36
	v_mov_b32_e32 v25, v36
	v_mov_b32_e32 v26, v36
	v_mov_b32_e32 v27, v36
	v_mov_b32_e32 v12, v36
	v_mov_b32_e32 v13, v36
	v_mov_b32_e32 v14, v36
	v_mov_b32_e32 v15, v36
	v_mov_b32_e32 v16, v36
	v_mov_b32_e32 v17, v36
	v_mov_b32_e32 v18, v36
	v_mov_b32_e32 v19, v36
	v_mov_b32_e32 v4, v36
	v_mov_b32_e32 v5, v36
	v_mov_b32_e32 v6, v36
	v_mov_b32_e32 v7, v36
	v_mov_b32_e32 v8, v36
	v_mov_b32_e32 v9, v36
	v_mov_b32_e32 v10, v36
	v_mov_b32_e32 v11, v36
	v_mov_b32_e32 v60, v36
	v_mov_b32_e32 v61, v36
	v_mov_b32_e32 v62, v36
	v_mov_b32_e32 v63, v36
	v_mov_b32_e32 v64, v36
	v_mov_b32_e32 v65, v36
	v_mov_b32_e32 v66, v36
	v_mov_b32_e32 v67, v36
	v_mov_b32_e32 v52, v36
	v_mov_b32_e32 v53, v36
	v_mov_b32_e32 v54, v36
	v_mov_b32_e32 v55, v36
	v_mov_b32_e32 v56, v36
	v_mov_b32_e32 v57, v36
	v_mov_b32_e32 v58, v36
	v_mov_b32_e32 v59, v36
	v_mov_b32_e32 v44, v36
	v_mov_b32_e32 v45, v36
	v_mov_b32_e32 v46, v36
	v_mov_b32_e32 v47, v36
	v_mov_b32_e32 v48, v36
	v_mov_b32_e32 v49, v36
	v_mov_b32_e32 v50, v36
	v_mov_b32_e32 v51, v36
	v_mov_b32_e32 v28, v36
	v_mov_b32_e32 v29, v36
	v_mov_b32_e32 v30, v36
	v_mov_b32_e32 v31, v36
	v_mov_b32_e32 v32, v36
	v_mov_b32_e32 v33, v36
	v_mov_b32_e32 v34, v36
	v_mov_b32_e32 v35, v36
	v_mov_b32_e32 v102, v36
	v_mov_b32_e32 v103, v36
	v_mov_b32_e32 v104, v36
	v_mov_b32_e32 v105, v36
	v_mov_b32_e32 v106, v36
	v_mov_b32_e32 v107, v36
	v_mov_b32_e32 v108, v36
	v_mov_b32_e32 v109, v36
	v_mov_b32_e32 v86, v36
	v_mov_b32_e32 v87, v36
	v_mov_b32_e32 v88, v36
	v_mov_b32_e32 v89, v36
	v_mov_b32_e32 v90, v36
	v_mov_b32_e32 v91, v36
	v_mov_b32_e32 v92, v36
	v_mov_b32_e32 v93, v36
	s_waitcnt lgkmcnt(0)
	v_mov_b32_e32 v78, v36
	v_mov_b32_e32 v79, v36
	v_mov_b32_e32 v80, v36
	v_mov_b32_e32 v81, v36
	v_mov_b32_e32 v82, v36
	v_mov_b32_e32 v83, v36
	v_mov_b32_e32 v84, v36
	v_mov_b32_e32 v85, v36
	v_mov_b32_e32 v70, v36
	v_mov_b32_e32 v71, v36
	v_mov_b32_e32 v72, v36
	v_mov_b32_e32 v73, v36
	v_mov_b32_e32 v74, v36
	v_mov_b32_e32 v75, v36
	v_mov_b32_e32 v76, v36
	v_mov_b32_e32 v77, v36
	v_mov_b32_e32 v126, v36
	v_mov_b32_e32 v127, v36
	v_mov_b32_e32 v128, v36
	v_mov_b32_e32 v129, v36
	v_mov_b32_e32 v130, v36
	v_mov_b32_e32 v131, v36
	v_mov_b32_e32 v132, v36
	v_mov_b32_e32 v133, v36
	v_mov_b32_e32 v118, v36
	v_mov_b32_e32 v119, v36
	v_mov_b32_e32 v120, v36
	v_mov_b32_e32 v121, v36
	v_mov_b32_e32 v122, v36
	v_mov_b32_e32 v123, v36
	v_mov_b32_e32 v124, v36
	v_mov_b32_e32 v125, v36
	v_mov_b32_e32 v110, v36
	v_mov_b32_e32 v111, v36
	v_mov_b32_e32 v112, v36
	v_mov_b32_e32 v113, v36
	v_mov_b32_e32 v114, v36
	v_mov_b32_e32 v115, v36
	v_mov_b32_e32 v116, v36
	v_mov_b32_e32 v117, v36
	v_mov_b32_e32 v94, v36
	v_mov_b32_e32 v95, v36
	v_mov_b32_e32 v96, v36
	v_mov_b32_e32 v97, v36
	v_mov_b32_e32 v98, v36
	v_mov_b32_e32 v99, v36
	v_mov_b32_e32 v100, v36
	v_mov_b32_e32 v101, v36
	s_barrier

.LBB0_3510:
	s_and_b32 s18, s8, 3
	s_mul_i32 s3, s16, 0x160000
	v_lshrrev_b32_e32 v4, 3, v0
	s_mul_hi_i32 s2, s16, 0x160000
	s_add_u32 s3, s12, s3
	v_and_b32_e32 v5, 32, v4
	v_lshlrev_b32_e32 v6, 1, v2
	v_lshrrev_b32_e32 v0, 5, v0
	s_addc_u32 s5, s13, s2
	s_lshl_b32 s2, s9, 1
	v_and_b32_e32 v6, 24, v6
	v_and_b32_e32 v2, 3, v2
	v_bitop3_b32 v0, v5, 36, v0 bitop3:0xc8
	s_add_u32 s2, s3, s2
	v_and_or_b32 v3, v4, 48, v3
	v_lshrrev_b32_e32 v4, 1, v147
	v_or3_b32 v0, v0, v2, v6
	s_addc_u32 s3, s5, 0
	s_mul_i32 s5, s18, 0x160000
	v_and_or_b32 v1, v1, 32, v4
	v_mul_u32_u24_e32 v3, 0xb00, v3
	v_mul_u32_u24_e32 v0, 0xb00, v0
	s_add_u32 s5, s34, s5
	v_or_b32_e32 v3, v1, v3
	v_or_b32_e32 v0, v0, v1
	v_lshlrev_b32_e32 v1, 1, v144
	s_addc_u32 s8, s35, 0
	v_and_b32_e32 v1, 4, v1
	s_movk_i32 s9, 0xe0
	s_lshl_b32 s4, s4, 1
	v_and_or_b32 v1, v145, s9, v1
	s_add_u32 s4, s5, s4
	v_lshlrev_b32_e32 v130, 1, v0
	v_lshlrev_b32_e32 v0, 5, v144
	v_or3_b32 v1, v1, v2, v6
	s_addc_u32 s5, s8, 0
	s_add_i32 s34, s27, 0
	v_and_or_b32 v0, v0, 32, v4
	v_mul_i32_i24_e32 v2, 0xb00, v146
	v_mul_u32_u24_e32 v1, 0xb00, v1
	s_add_i32 m0, s34, 0x10400
	v_or_b32_e32 v2, v2, v0
	v_or_b32_e32 v0, v1, v0
	global_load_lds_dwordx4 v130, s[4:5]
	s_add_i32 m0, s34, 0x12400
	v_lshlrev_b32_e32 v134, 1, v0
	s_add_u32 s8, s4, 0xb0000
	global_load_lds_dwordx4 v134, s[4:5]
	s_addc_u32 s9, s5, 0
	s_add_i32 m0, s34, 0x14400
	s_add_i32 s19, s34, 0x400
	global_load_lds_dwordx4 v130, s[8:9]
	s_add_i32 m0, s34, 0x16400
	s_add_i32 s20, s34, 0x2400
	v_lshlrev_b32_e32 v128, 1, v3
	global_load_lds_dwordx4 v134, s[8:9]
	s_mov_b32 m0, s19
	s_add_u32 s8, s2, 0xb0000
	v_lshlrev_b32_e32 v132, 1, v2
	global_load_lds_dwordx4 v128, s[2:3]
	s_mov_b32 m0, s20
	s_addc_u32 s9, s3, 0
	s_add_i32 s21, s34, 0x4400
	global_load_lds_dwordx4 v132, s[2:3]
	s_mov_b32 m0, s21
	s_add_i32 s22, s34, 0x6400
	global_load_lds_dwordx4 v128, s[8:9]
	s_mov_b32 m0, s22
	v_mov_b32_e32 v131, 0
	global_load_lds_dwordx4 v132, s[8:9]
	v_mov_b32_e32 v135, v131
	v_mov_b32_e32 v129, v131
	v_mov_b32_e32 v133, v131
	s_mov_b32 s9, 0
	v_lshl_add_u64 v[6:7], s[4:5], 0, v[130:131]
	v_lshl_add_u64 v[4:5], s[4:5], 0, v[134:135]
	v_lshl_add_u64 v[2:3], s[2:3], 0, v[128:129]
	v_lshl_add_u64 v[0:1], s[2:3], 0, v[132:133]
	s_mov_b64 s[10:11], 0x80
	s_add_i32 m0, s34, 0x18400
	v_lshl_add_u64 v[6:7], v[6:7], 0, s[10:11]
	global_load_lds_dwordx4 v[6:7], off
	v_lshl_add_u64 v[4:5], v[4:5], 0, s[10:11]
	s_add_i32 m0, s34, 0x1a400
	s_add_i32 s23, s34, 0x8400
	s_add_i32 s24, s34, 0xa400
	global_load_lds_dwordx4 v[4:5], off
	v_lshl_add_u64 v[2:3], v[2:3], 0, s[10:11]
	s_mov_b32 m0, s23
	s_add_u32 s12, s4, 0xb0080
	global_load_lds_dwordx4 v[2:3], off
	v_lshl_add_u64 v[0:1], v[0:1], 0, s[10:11]
	s_mov_b32 m0, s24
	s_addc_u32 s13, s5, 0
	global_load_lds_dwordx4 v[0:1], off
	s_add_i32 m0, s34, 0x1c400
	v_lshl_add_u64 v[0:1], s[12:13], 0, v[130:131]
	global_load_lds_dwordx4 v[0:1], off
	v_lshl_add_u64 v[0:1], s[12:13], 0, v[134:135]
	s_add_i32 m0, s34, 0x1e400
	s_nop 0
	global_load_lds_dwordx4 v[0:1], off
	s_cmp_lg_u32 s28, 1
	s_cbranch_scc1 .LBB0_3512
	s_barrier
.LBB0_3512:
	s_waitcnt vmcnt(8)
	s_barrier
	s_bitcmp0_b32 s17, 0
	s_cselect_b32 s8, 12, 10
	s_and_b64 s[12:13], s[14:15], exec
	s_waitcnt vmcnt(6)
	s_cselect_b32 s25, 22, s8
	s_add_i32 s35, 0, 0x10400
	s_add_i32 s37, 0, 0x14400
	s_add_i32 s39, 0, 0x18400
	s_add_i32 s8, 0, 0x1c400
	v_add_u32_e32 v136, s35, v143
	v_add_u32_e32 v137, s37, v143
	s_add_i32 s35, s35, s27
	s_add_i32 s37, s37, s27
	v_add_u32_e32 v139, s39, v143
	s_add_i32 s39, s39, s27
	s_add_i32 s27, s8, s27
	s_add_i32 s28, s25, -2
	v_add_u32_e32 v138, 0, v142
	s_add_i32 s29, s34, 0xc400
	s_add_i32 s34, s34, 0xe400
	s_add_i32 s36, s35, 0x2000
	s_add_i32 s38, s37, 0x2000
	v_add_u32_e32 v142, s8, v143
	s_add_i32 s40, s39, 0x2000
	s_add_i32 s41, s27, 0x2000
	s_mov_b32 s12, 0
	v_mov_b32_e32 v0, v131
	v_mov_b32_e32 v1, v131
	v_mov_b32_e32 v2, v131
	v_mov_b32_e32 v3, v131
	v_mov_b32_e32 v4, v131
	v_mov_b32_e32 v5, v131
	v_mov_b32_e32 v6, v131
	v_mov_b32_e32 v7, v131
	v_mov_b32_e32 v8, v131
	v_mov_b32_e32 v9, v131
	v_mov_b32_e32 v10, v131
	v_mov_b32_e32 v11, v131
	v_mov_b32_e32 v12, v131
	v_mov_b32_e32 v13, v131
	v_mov_b32_e32 v14, v131
	v_mov_b32_e32 v15, v131
	v_mov_b32_e32 v24, v131
	v_mov_b32_e32 v25, v131
	v_mov_b32_e32 v26, v131
	v_mov_b32_e32 v27, v131
	v_mov_b32_e32 v28, v131
	v_mov_b32_e32 v29, v131
	v_mov_b32_e32 v30, v131
	v_mov_b32_e32 v31, v131
	v_mov_b32_e32 v40, v131
	v_mov_b32_e32 v41, v131
	v_mov_b32_e32 v42, v131
	v_mov_b32_e32 v43, v131
	v_mov_b32_e32 v44, v131
	v_mov_b32_e32 v45, v131
	v_mov_b32_e32 v46, v131
	v_mov_b32_e32 v47, v131
	v_mov_b32_e32 v16, v131
	v_mov_b32_e32 v17, v131
	v_mov_b32_e32 v18, v131
	v_mov_b32_e32 v19, v131
	v_mov_b32_e32 v20, v131
	v_mov_b32_e32 v21, v131
	v_mov_b32_e32 v22, v131
	v_mov_b32_e32 v23, v131
	v_mov_b32_e32 v32, v131
	v_mov_b32_e32 v33, v131
	v_mov_b32_e32 v34, v131
	v_mov_b32_e32 v35, v131
	v_mov_b32_e32 v36, v131
	v_mov_b32_e32 v37, v131
	v_mov_b32_e32 v38, v131
	v_mov_b32_e32 v39, v131
	v_mov_b32_e32 v48, v131
	v_mov_b32_e32 v49, v131
	v_mov_b32_e32 v50, v131
	v_mov_b32_e32 v51, v131
	v_mov_b32_e32 v52, v131
	v_mov_b32_e32 v53, v131
	v_mov_b32_e32 v54, v131
	v_mov_b32_e32 v55, v131
	v_mov_b32_e32 v56, v131
	v_mov_b32_e32 v57, v131
	v_mov_b32_e32 v58, v131
	v_mov_b32_e32 v59, v131
	v_mov_b32_e32 v60, v131
	v_mov_b32_e32 v61, v131
	v_mov_b32_e32 v62, v131
	v_mov_b32_e32 v63, v131
	v_mov_b32_e32 v64, v131
	v_mov_b32_e32 v65, v131
	v_mov_b32_e32 v66, v131
	v_mov_b32_e32 v67, v131
	v_mov_b32_e32 v68, v131
	v_mov_b32_e32 v69, v131
	v_mov_b32_e32 v70, v131
	v_mov_b32_e32 v71, v131
	v_mov_b32_e32 v72, v131
	v_mov_b32_e32 v73, v131
	v_mov_b32_e32 v74, v131
	v_mov_b32_e32 v75, v131
	v_mov_b32_e32 v76, v131
	v_mov_b32_e32 v77, v131
	v_mov_b32_e32 v78, v131
	v_mov_b32_e32 v79, v131
	v_mov_b32_e32 v88, v131
	v_mov_b32_e32 v89, v131
	v_mov_b32_e32 v90, v131
	v_mov_b32_e32 v91, v131
	v_mov_b32_e32 v92, v131
	v_mov_b32_e32 v93, v131
	v_mov_b32_e32 v94, v131
	v_mov_b32_e32 v95, v131
	v_mov_b32_e32 v104, v131
	v_mov_b32_e32 v105, v131
	v_mov_b32_e32 v106, v131
	v_mov_b32_e32 v107, v131
	v_mov_b32_e32 v108, v131
	v_mov_b32_e32 v109, v131
	v_mov_b32_e32 v110, v131
	v_mov_b32_e32 v111, v131
	v_mov_b32_e32 v80, v131
	v_mov_b32_e32 v81, v131
	v_mov_b32_e32 v82, v131
	v_mov_b32_e32 v83, v131
	v_mov_b32_e32 v84, v131
	v_mov_b32_e32 v85, v131
	v_mov_b32_e32 v86, v131
	v_mov_b32_e32 v87, v131
	v_mov_b32_e32 v96, v131
	v_mov_b32_e32 v97, v131
	v_mov_b32_e32 v98, v131
	v_mov_b32_e32 v99, v131
	v_mov_b32_e32 v100, v131
	v_mov_b32_e32 v101, v131
	v_mov_b32_e32 v102, v131
	v_mov_b32_e32 v103, v131
	v_mov_b32_e32 v112, v131
	v_mov_b32_e32 v113, v131
	v_mov_b32_e32 v114, v131
	v_mov_b32_e32 v115, v131
	v_mov_b32_e32 v116, v131
	v_mov_b32_e32 v117, v131
	v_mov_b32_e32 v118, v131
	v_mov_b32_e32 v119, v131
	v_mov_b32_e32 v120, v131
	v_mov_b32_e32 v121, v131
	v_mov_b32_e32 v122, v131
	v_mov_b32_e32 v123, v131
	v_mov_b32_e32 v124, v131
	v_mov_b32_e32 v125, v131
	v_mov_b32_e32 v126, v131
	v_mov_b32_e32 v127, v131
	s_barrier
